# EpiMla rope-address slices hoisted one block ahead (lane-constant ops duplicated)
# baseline (speedup 1.0000x reference)
; #define PIN(i) ((const float*)(const GASP float*)karg_q(i))
;     __device__ __forceinline__ void operator()(const f32x4 (&acc)[2][2][4][2], const Unit& u, int wr, int wc, int, int) const {
;         const int lane_ = ::otid() & 63, fr = lane_ & 15, fq = lane_ >> 4;
;         unsigned char* ws = PWS;
;         const bool isq = u.pn < 3; const int head = (isq ? u.pn : u.pn - 3) * 2 + (wc >> 1), kind = wc & 1;
;         const bool latent = u.pm < 128, is_v = !isq && kind == 1, is_rope = isq && kind == 1, rot = is_rope && latent;
;         const int sbj = is_rope ? 8 : 32;
;         const float* gsrc = is_v ? (const float*)(ws + WS_ROPE) + 1024 : (isq ? PIN(16) + l * 96 : PIN(17) + l * 96);
;         const float* g = gsrc + (is_rope ? 64 + 16 * (fq & 1) : 8 * fq);
;         const float* rope = (const float*)(ws + WS_ROPE);
;         bf16_t* obase = (bf16_t*)(ws + (is_v ? WS_MV : (isq ? WS_MQ : WS_MK)));
;         const int ostride = is_v ? 384 : 576;
;         const int ocol = is_v ? head * 64 + 8 * fq : head * 96 + (is_rope ? 64 + 16 * (fq & 1) : 8 * fq);
;         const float inv_cnt = is_rope ? (1.0f / 32.0f) : (1.0f / 64.0f), sc = isq ? MLA_SCALE : 1.0f;
;         const bool st_ok = !is_rope || fq < 2;
;         const int rowb = u.pm * BM + wr * 64 + fr;
; #pragma unroll
;         for (int ai = 0; ai < 2; ++ai)
; #pragma unroll
;             for (int m = 0; m < 4; ++m) {
;                 const int row = rowb + ai * HALF + m * 16;
;                 float ss = 0.f;
; #pragma unroll
;                 for (int j = 0; j < 4; ++j) ss += acc[ai][0][m][0][j] * acc[ai][0][m][0][j] + acc[ai][0][m][1][j] * acc[ai][0][m][1][j] + acc[ai][1][m][0][j] * acc[ai][1][m][0][j] + acc[ai][1][m][1][j] * acc[ai][1][m][1][j];
;                 ss += ::swz<16>(ss); ss = ::x32_sum(ss);
;                 float rs = rsqrtf(ss * inv_cnt + 1e-6f) * sc; rs = is_v ? 1.0f : rs;
;                 const int pos = row & 2047, pp = rot ? ((fq & 1) ? (pos & 63) : (pos >> 6)) : 0;
;                 const float* rt = rope + pp * 16;
;                 bf16_t* dst = obase + (unsigned)(row * ostride + ocol);
; #pragma unroll
;                 for (int n = 0; n < 2; ++n) {
;                     const f32x4 g1 = *(const f32x4*)(g + 4 * n), g2 = *(const f32x4*)(g + sbj + 4 * n);
;                     const f32x4 t0 = *(const f32x4*)(rt + 8 * n), t1 = *(const f32x4*)(rt + 8 * n + 4);
.LBB0_669:
	v_and_b32_e32 v161, 15, v140
	v_mov_b32_e32 v140, 0x3c800000
	v_mov_b32_e32 v143, 0x3d000000
	v_lshlrev_b32_e32 v138, 2, v138
	v_mov_b32_e32 v139, v0
	v_cndmask_b32_e64 v159, v140, v143, s[42:43]
	v_mov_b32_e32 v140, 0x3e16c740
	v_lshl_add_u64 v[138:139], s[2:3], 0, v[138:139]
	global_load_dwordx4 v[172:175], v[138:139], off
	s_and_b64 s[2:3], s[40:41], exec
	v_cndmask_b32_e64 v143, 1.0, v140, s[40:41]
	v_cmp_gt_u32_e64 s[40:41], 2, v141
	v_mul_f32_e32 v140, v118, v118
	v_mul_f32_e32 v141, v119, v119
	v_fmac_f32_e32 v140, v126, v126
	v_fmac_f32_e32 v141, v127, v127
	v_fmac_f32_e32 v140, v122, v122
	v_fmac_f32_e32 v141, v123, v123
	v_fmac_f32_e32 v140, v114, v114
	v_fmac_f32_e32 v141, v115, v115
	v_add_f32_e32 v140, v140, v141
	v_mul_f32_e32 v141, v120, v120
	v_fmac_f32_e32 v141, v128, v128
	s_cselect_b32 s3, 0x16b98000, s76
	v_fmac_f32_e32 v141, v124, v124
	s_cselect_b32 s2, 0, 0
	s_add_u32 s60, s56, s3
	v_fmac_f32_e32 v141, v116, v116
	s_addc_u32 s61, s57, s2
	v_add_f32_e32 v140, v141, v140
	v_mul_f32_e32 v141, v121, v121
	s_cmpk_lt_i32 s54, 0x80
	v_fmac_f32_e32 v141, v129, v129
	s_cselect_b64 s[2:3], -1, 0
	v_fmac_f32_e32 v141, v125, v125
	s_and_b64 vcc, s[42:43], s[2:3]
	s_xor_b64 s[2:3], s[42:43], -1
	v_fmac_f32_e32 v141, v117, v117
	s_or_b64 s[20:21], s[2:3], s[40:41]
	v_cmp_eq_u32_e64 s[40:41], 0, v144
	v_add_f32_e32 v144, v141, v140
	ds_swizzle_b32 v145, v144 offset:swizzle(SWAP,16)
	s_lshl_b32 s2, s54, 8
	s_add_i32 s5, s2, s78
	s_and_b64 s[2:3], s[42:43], exec
	s_cselect_b32 s16, 8, 32
	s_waitcnt lgkmcnt(0)
	v_add_f32_e32 v158, v144, v145
	s_lshl_b32 s54, s16, 2
	v_mov_b32_e32 v162, v158
	v_or_b32_e32 v160, s5, v161
	v_lshl_add_u64 v[140:141], v[138:139], 0, s[54:55]
	s_bfe_u32 s17, s5, 0x50006
	v_mov_b32_e32 v248, s17
	v_cndmask_b32_e64 v248, v161, v248, s[40:41]
	v_lshlrev_b32_e32 v248, 4, v248
	v_cndmask_b32_e32 v248, 0, v248, vcc
	v_lshlrev_b32_e32 v249, 2, v248
	global_load_dwordx4 v[176:179], v249, s[22:23]
	global_load_dwordx4 v[180:183], v249, s[22:23] offset:16
	global_load_dwordx4 v[184:187], v[140:141], off
	global_load_dwordx4 v[188:191], v[138:139], off offset:16
	global_load_dwordx4 v[192:195], v249, s[22:23] offset:32
	global_load_dwordx4 v[196:199], v249, s[22:23] offset:48
	global_load_dwordx4 v[200:203], v[140:141], off offset:16
	v_permlane32_swap_b32_e32 v158, v162
	s_and_saveexec_b64 s[2:3], s[20:21]
	v_add_f32_e32 v146, v158, v162
	v_mad_u64_u32 v[144:145], s[42:43], s26, v160, v[142:143]
	v_fmaak_f32 v146, v159, v146, 0x358637bd
	v_cmp_gt_f32_e64 s[42:43], s88, v146
	v_mul_f32_e32 v147, 0x4b800000, v146
	v_mov_b32_e32 v145, v0
	v_cndmask_b32_e64 v146, v146, v147, s[42:43]
	v_rsq_f32_e32 v146, v146
	v_lshl_add_u64 v[156:157], v[144:145], 1, s[60:61]
	s_lshl_b32 s54, s16, 1
	v_lshl_add_u64 v[144:145], v[156:157], 0, s[54:55]
	v_mul_f32_e32 v147, 0x45800000, v146
	v_cndmask_b32_e64 v146, v146, v147, s[42:43]
	v_mul_f32_e32 v146, v143, v146
	v_cndmask_b32_e64 v158, v146, 1.0, s[50:51]
	v_pk_mul_f32 v[146:147], v[128:129], v[158:159] op_sel_hi:[1,0]
	v_pk_mul_f32 v[148:149], v[126:127], v[158:159] op_sel_hi:[1,0]
	global_load_dwordx4 v[204:207], v[138:139], off
	v_pk_mul_f32 v[150:151], v[122:123], v[158:159] op_sel_hi:[1,0]
	v_pk_mul_f32 v[152:153], v[124:125], v[158:159] op_sel_hi:[1,0]
	s_waitcnt vmcnt(8)
	v_pk_mul_f32 v[148:149], v[148:149], v[172:173]
	v_pk_mul_f32 v[146:147], v[146:147], v[174:175]
	v_or_b32_e32 v251, 16, v161
	v_mov_b32_e32 v218, s17
	v_cndmask_b32_e64 v218, v251, v218, s[40:41]
	v_lshlrev_b32_e32 v218, 4, v218
	v_cndmask_b32_e32 v218, 0, v218, vcc
	v_lshlrev_b32_e32 v216, 2, v218
	global_load_dwordx4 v[172:175], v216, s[22:23]
	global_load_dwordx4 v[212:215], v216, s[22:23] offset:16
	global_load_dwordx4 v[224:227], v[140:141], off
	s_waitcnt vmcnt(9)
	v_mov_b32_e32 v166, v180
	s_waitcnt vmcnt(8)
	v_pk_mul_f32 v[124:125], v[152:153], v[186:187]
	v_pk_mul_f32 v[122:123], v[150:151], v[184:185]
	v_mov_b32_e32 v150, v176
	v_mov_b32_e32 v151, v178
	v_mov_b32_e32 v167, v182
	v_mov_b32_e32 v182, v181
	v_mov_b32_e32 v178, v177
	v_pk_mul_f32 v[152:153], v[150:151], v[122:123]
	v_pk_mul_f32 v[168:169], v[166:167], v[124:125]
	v_pk_mul_f32 v[122:123], v[178:179], v[122:123]
	v_pk_mul_f32 v[124:125], v[182:183], v[124:125]
	v_pk_fma_f32 v[122:123], v[148:149], v[150:151], v[122:123] neg_lo:[0,0,1] neg_hi:[0,0,1]
	v_pk_fma_f32 v[124:125], v[146:147], v[166:167], v[124:125] neg_lo:[0,0,1] neg_hi:[0,0,1]
	v_pk_fma_f32 v[162:163], v[146:147], v[182:183], v[168:169]
	v_pk_fma_f32 v[126:127], v[148:149], v[178:179], v[152:153]
	v_cvt_pk_bf16_f32 v240, v122, v123
	v_cvt_pk_bf16_f32 v241, v124, v125
	v_cvt_pk_bf16_f32 v244, v126, v127
	v_cvt_pk_bf16_f32 v245, v162, v163
	v_pk_mul_f32 v[122:123], v[120:121], v[158:159] op_sel_hi:[1,0]
	v_pk_mul_f32 v[124:125], v[118:119], v[158:159] op_sel_hi:[1,0]
	global_load_dwordx4 v[176:179], v[138:139], off offset:16
	v_pk_mul_f32 v[146:147], v[114:115], v[158:159] op_sel_hi:[1,0]
	v_pk_mul_f32 v[148:149], v[116:117], v[158:159] op_sel_hi:[1,0]
	s_waitcnt vmcnt(8)
	v_pk_mul_f32 v[126:127], v[124:125], v[188:189]
	v_pk_mul_f32 v[128:129], v[122:123], v[190:191]
	global_load_dwordx4 v[180:183], v216, s[22:23] offset:32
	global_load_dwordx4 v[184:187], v216, s[22:23] offset:48
	global_load_dwordx4 v[188:191], v[140:141], off offset:16
	s_waitcnt vmcnt(9)
	v_mov_b32_e32 v150, v196
	s_waitcnt vmcnt(8)
	v_pk_mul_f32 v[116:117], v[148:149], v[202:203]
	v_pk_mul_f32 v[114:115], v[146:147], v[200:201]
	v_mov_b32_e32 v146, v192
	v_mov_b32_e32 v147, v194
	v_mov_b32_e32 v151, v198
	v_mov_b32_e32 v198, v197
	v_mov_b32_e32 v194, v193
	v_pk_mul_f32 v[148:149], v[146:147], v[114:115]
	v_pk_mul_f32 v[152:153], v[150:151], v[116:117]
	v_pk_mul_f32 v[114:115], v[194:195], v[114:115]
	v_pk_mul_f32 v[116:117], v[198:199], v[116:117]
	v_pk_fma_f32 v[114:115], v[126:127], v[146:147], v[114:115] neg_lo:[0,0,1] neg_hi:[0,0,1]
	v_pk_fma_f32 v[116:117], v[128:129], v[150:151], v[116:117] neg_lo:[0,0,1] neg_hi:[0,0,1]
	v_pk_fma_f32 v[122:123], v[128:129], v[198:199], v[152:153]
	v_pk_fma_f32 v[118:119], v[126:127], v[194:195], v[148:149]
	v_cvt_pk_bf16_f32 v242, v114, v115
	v_cvt_pk_bf16_f32 v243, v116, v117
	global_store_dwordx4 v[156:157], v[240:243], off
	v_cvt_pk_bf16_f32 v246, v118, v119
	v_cvt_pk_bf16_f32 v247, v122, v123
	global_store_dwordx4 v[144:145], v[244:247], off
; template <int K> __device__ __forceinline__ float swz(float v) { return __int_as_float(__builtin_amdgcn_ds_swizzle(__float_as_int(v), (K << 10) | 0x1f)); }
; __device__ __forceinline__ float x32_sum(float v) { auto r = __builtin_amdgcn_permlane32_swap(__float_as_uint(v), __float_as_uint(v), false, false); return __uint_as_float(r[0]) + __uint_as_float(r[1]); }
; __device__ __forceinline__ unsigned cvt_pk_bf16(float lo, float hi) { const f32x2c f = {lo, hi}; return __builtin_bit_cast(unsigned, __builtin_convertvector(f, bf16x2c)); }
;     __device__ __forceinline__ void operator()(const f32x4 (&acc)[2][2][4][2], const Unit& u, int wr, int wc, int, int) const {
;     ...
;             for (int m = 0; m < 4; ++m) {
;                 const int row = rowb + ai * HALF + m * 16;
;                 float ss = 0.f;
; #pragma unroll
;                 for (int j = 0; j < 4; ++j) ss += acc[ai][0][m][0][j] * acc[ai][0][m][0][j] + acc[ai][0][m][1][j] * acc[ai][0][m][1][j] + acc[ai][1][m][0][j] * acc[ai][1][m][0][j] + acc[ai][1][m][1][j] * acc[ai][1][m][1][j];
;                 ss += ::swz<16>(ss); ss = ::x32_sum(ss);
;                 float rs = rsqrtf(ss * inv_cnt + 1e-6f) * sc; rs = is_v ? 1.0f : rs;
;                 const int pos = row & 2047, pp = rot ? ((fq & 1) ? (pos & 63) : (pos >> 6)) : 0;
;                 const float* rt = rope + pp * 16;
;                 bf16_t* dst = obase + (unsigned)(row * ostride + ocol);
; #pragma unroll
;                 for (int n = 0; n < 2; ++n) {
;                     const f32x4 g1 = *(const f32x4*)(g + 4 * n), g2 = *(const f32x4*)(g + sbj + 4 * n);
;                     const f32x4 t0 = *(const f32x4*)(rt + 8 * n), t1 = *(const f32x4*)(rt + 8 * n + 4);
;                     const f32x4 c = (f32x4){t0[0], t0[2], t1[0], t1[2]}, s = (f32x4){t0[1], t0[3], t1[1], t1[3]};
;                     const f32x4 a1 = acc[ai][0][m][n] * rs * g1, a2 = acc[ai][1][m][n] * rs * g2;
;                     const f32x4 o1 = a1 * c - a2 * s, o2 = a1 * s + a2 * c;
;                     if (st_ok) { u32x2 w; w.x = cvt_pk_bf16(o1[0], o1[1]); w.y = cvt_pk_bf16(o1[2], o1[3]); *(u32x2*)(dst + 4 * n) = w;
;                         w.x = cvt_pk_bf16(o2[0], o2[1]); w.y = cvt_pk_bf16(o2[2], o2[3]); *(u32x2*)(dst + sbj + 4 * n) = w; }
;                 }
;                 asm volatile("" ::: "memory");
.LBB0_671:
	s_or_b64 exec, exec, s[2:3]
	v_mul_f32_e32 v114, v102, v102
	v_mul_f32_e32 v115, v103, v103
	v_fmac_f32_e32 v114, v110, v110
	v_fmac_f32_e32 v115, v111, v111
	v_fmac_f32_e32 v114, v106, v106
	v_fmac_f32_e32 v115, v107, v107
	v_fmac_f32_e32 v114, v98, v98
	v_fmac_f32_e32 v115, v99, v99
	v_add_f32_e32 v114, v114, v115
	v_mul_f32_e32 v115, v104, v104
	v_fmac_f32_e32 v115, v112, v112
	v_fmac_f32_e32 v115, v108, v108
	v_fmac_f32_e32 v115, v100, v100
	v_add_f32_e32 v114, v115, v114
	v_mul_f32_e32 v115, v105, v105
	v_fmac_f32_e32 v115, v113, v113
	v_fmac_f32_e32 v115, v109, v109
	v_fmac_f32_e32 v115, v101, v101
	v_add_f32_e32 v114, v115, v114
	ds_swizzle_b32 v115, v114 offset:swizzle(SWAP,16)
	v_or_b32_e32 v119, 16, v161
	s_waitcnt lgkmcnt(0)
	v_add_f32_e32 v118, v114, v115
	v_mov_b32_e32 v120, v118
	s_nop 1
	v_permlane32_swap_b32_e32 v118, v120
	s_and_saveexec_b64 s[2:3], s[20:21]
	v_or_b32_e32 v114, 16, v160
	v_add_f32_e32 v118, v118, v120
	v_mad_u64_u32 v[114:115], s[42:43], s26, v114, v[142:143]
	v_fmaak_f32 v118, v159, v118, 0x358637bd
	v_cmp_gt_f32_e64 s[42:43], s88, v118
	v_mul_f32_e32 v120, 0x4b800000, v118
	v_mov_b32_e32 v115, v0
	v_cndmask_b32_e64 v118, v118, v120, s[42:43]
	v_rsq_f32_e32 v118, v118
	v_lshl_add_u64 v[116:117], v[114:115], 1, s[60:61]
	s_lshl_b32 s54, s16, 1
	v_lshl_add_u64 v[114:115], v[116:117], 0, s[54:55]
	v_mul_f32_e32 v120, 0x45800000, v118
	v_cndmask_b32_e64 v118, v118, v120, s[42:43]
	v_mul_f32_e32 v118, v143, v118
	v_cndmask_b32_e64 v118, v118, 1.0, s[50:51]
	v_pk_mul_f32 v[120:121], v[112:113], v[118:119] op_sel_hi:[1,0]
	v_pk_mul_f32 v[122:123], v[110:111], v[118:119] op_sel_hi:[1,0]
	global_load_dwordx4 v[192:195], v[138:139], off
	v_pk_mul_f32 v[128:129], v[106:107], v[118:119] op_sel_hi:[1,0]
	v_pk_mul_f32 v[144:145], v[108:109], v[118:119] op_sel_hi:[1,0]
	s_waitcnt vmcnt(10)
	v_pk_mul_f32 v[124:125], v[122:123], v[204:205]
	v_pk_mul_f32 v[126:127], v[120:121], v[206:207]
	v_or_b32_e32 v248, 32, v161
	v_mov_b32_e32 v250, s17
	v_cndmask_b32_e64 v250, v248, v250, s[40:41]
	v_lshlrev_b32_e32 v250, 4, v250
	v_cndmask_b32_e32 v250, 0, v250, vcc
	v_lshlrev_b32_e32 v249, 2, v250
	global_load_dwordx4 v[196:199], v249, s[22:23]
	global_load_dwordx4 v[200:203], v249, s[22:23] offset:16
	global_load_dwordx4 v[204:207], v[140:141], off
	s_waitcnt vmcnt(11)
	v_mov_b32_e32 v146, v212
	s_waitcnt vmcnt(10)
	v_pk_mul_f32 v[108:109], v[144:145], v[226:227]
	v_pk_mul_f32 v[106:107], v[128:129], v[224:225]
	v_mov_b32_e32 v128, v172
	v_mov_b32_e32 v129, v174
	v_mov_b32_e32 v147, v214
	v_mov_b32_e32 v214, v213
	v_mov_b32_e32 v174, v173
	v_pk_mul_f32 v[144:145], v[128:129], v[106:107]
	v_pk_mul_f32 v[148:149], v[146:147], v[108:109]
	v_pk_mul_f32 v[106:107], v[174:175], v[106:107]
	v_pk_mul_f32 v[108:109], v[214:215], v[108:109]
	v_pk_fma_f32 v[106:107], v[124:125], v[128:129], v[106:107] neg_lo:[0,0,1] neg_hi:[0,0,1]
	v_pk_fma_f32 v[108:109], v[126:127], v[146:147], v[108:109] neg_lo:[0,0,1] neg_hi:[0,0,1]
	v_pk_fma_f32 v[120:121], v[126:127], v[214:215], v[148:149]
	v_pk_fma_f32 v[110:111], v[124:125], v[174:175], v[144:145]
	v_cvt_pk_bf16_f32 v240, v106, v107
	v_cvt_pk_bf16_f32 v241, v108, v109
	v_cvt_pk_bf16_f32 v244, v110, v111
	v_cvt_pk_bf16_f32 v245, v120, v121
	v_pk_mul_f32 v[106:107], v[104:105], v[118:119] op_sel_hi:[1,0]
	v_pk_mul_f32 v[108:109], v[102:103], v[118:119] op_sel_hi:[1,0]
	global_load_dwordx4 v[172:175], v[138:139], off offset:16
	v_pk_mul_f32 v[120:121], v[98:99], v[118:119] op_sel_hi:[1,0]
	v_pk_mul_f32 v[122:123], v[100:101], v[118:119] op_sel_hi:[1,0]
	s_waitcnt vmcnt(10)
	v_pk_mul_f32 v[110:111], v[108:109], v[176:177]
	v_pk_mul_f32 v[112:113], v[106:107], v[178:179]
	global_load_dwordx4 v[176:179], v249, s[22:23] offset:32
	global_load_dwordx4 v[212:215], v249, s[22:23] offset:48
	global_load_dwordx4 v[224:227], v[140:141], off offset:16
	s_waitcnt vmcnt(11)
	v_mov_b32_e32 v124, v184
	s_waitcnt vmcnt(10)
	v_pk_mul_f32 v[100:101], v[122:123], v[190:191]
	v_pk_mul_f32 v[98:99], v[120:121], v[188:189]
	v_mov_b32_e32 v120, v180
	v_mov_b32_e32 v121, v182
	v_mov_b32_e32 v125, v186
	v_mov_b32_e32 v186, v185
	v_mov_b32_e32 v182, v181
	v_pk_mul_f32 v[122:123], v[120:121], v[98:99]
	v_pk_mul_f32 v[126:127], v[124:125], v[100:101]
	v_pk_mul_f32 v[98:99], v[182:183], v[98:99]
	v_pk_mul_f32 v[100:101], v[186:187], v[100:101]
	v_pk_fma_f32 v[98:99], v[110:111], v[120:121], v[98:99] neg_lo:[0,0,1] neg_hi:[0,0,1]
	v_pk_fma_f32 v[100:101], v[112:113], v[124:125], v[100:101] neg_lo:[0,0,1] neg_hi:[0,0,1]
	v_pk_fma_f32 v[106:107], v[112:113], v[186:187], v[126:127]
	v_pk_fma_f32 v[102:103], v[110:111], v[182:183], v[122:123]
	v_cvt_pk_bf16_f32 v242, v98, v99
	v_cvt_pk_bf16_f32 v243, v100, v101
	global_store_dwordx4 v[116:117], v[240:243], off
	v_cvt_pk_bf16_f32 v246, v102, v103
	v_cvt_pk_bf16_f32 v247, v106, v107
	global_store_dwordx4 v[114:115], v[244:247], off
; template <int K> __device__ __forceinline__ float swz(float v) { return __int_as_float(__builtin_amdgcn_ds_swizzle(__float_as_int(v), (K << 10) | 0x1f)); }
; __device__ __forceinline__ float x32_sum(float v) { auto r = __builtin_amdgcn_permlane32_swap(__float_as_uint(v), __float_as_uint(v), false, false); return __uint_as_float(r[0]) + __uint_as_float(r[1]); }
; __device__ __forceinline__ unsigned cvt_pk_bf16(float lo, float hi) { const f32x2c f = {lo, hi}; return __builtin_bit_cast(unsigned, __builtin_convertvector(f, bf16x2c)); }
;     __device__ __forceinline__ void operator()(const f32x4 (&acc)[2][2][4][2], const Unit& u, int wr, int wc, int, int) const {
;     ...
;             for (int m = 0; m < 4; ++m) {
;                 const int row = rowb + ai * HALF + m * 16;
;                 float ss = 0.f;
; #pragma unroll
;                 for (int j = 0; j < 4; ++j) ss += acc[ai][0][m][0][j] * acc[ai][0][m][0][j] + acc[ai][0][m][1][j] * acc[ai][0][m][1][j] + acc[ai][1][m][0][j] * acc[ai][1][m][0][j] + acc[ai][1][m][1][j] * acc[ai][1][m][1][j];
;                 ss += ::swz<16>(ss); ss = ::x32_sum(ss);
;                 float rs = rsqrtf(ss * inv_cnt + 1e-6f) * sc; rs = is_v ? 1.0f : rs;
;                 const int pos = row & 2047, pp = rot ? ((fq & 1) ? (pos & 63) : (pos >> 6)) : 0;
;                 const float* rt = rope + pp * 16;
;                 bf16_t* dst = obase + (unsigned)(row * ostride + ocol);
; #pragma unroll
;                 for (int n = 0; n < 2; ++n) {
;                     const f32x4 g1 = *(const f32x4*)(g + 4 * n), g2 = *(const f32x4*)(g + sbj + 4 * n);
;                     const f32x4 t0 = *(const f32x4*)(rt + 8 * n), t1 = *(const f32x4*)(rt + 8 * n + 4);
;                     const f32x4 c = (f32x4){t0[0], t0[2], t1[0], t1[2]}, s = (f32x4){t0[1], t0[3], t1[1], t1[3]};
;                     const f32x4 a1 = acc[ai][0][m][n] * rs * g1, a2 = acc[ai][1][m][n] * rs * g2;
;                     const f32x4 o1 = a1 * c - a2 * s, o2 = a1 * s + a2 * c;
;                     if (st_ok) { u32x2 w; w.x = cvt_pk_bf16(o1[0], o1[1]); w.y = cvt_pk_bf16(o1[2], o1[3]); *(u32x2*)(dst + 4 * n) = w;
;                         w.x = cvt_pk_bf16(o2[0], o2[1]); w.y = cvt_pk_bf16(o2[2], o2[3]); *(u32x2*)(dst + sbj + 4 * n) = w; }
;                 }
;                 asm volatile("" ::: "memory");
.LBB0_673:
	s_or_b64 exec, exec, s[2:3]
	v_mul_f32_e32 v98, v86, v86
	v_mul_f32_e32 v99, v87, v87
	v_fmac_f32_e32 v98, v94, v94
	v_fmac_f32_e32 v99, v95, v95
	v_fmac_f32_e32 v98, v90, v90
	v_fmac_f32_e32 v99, v91, v91
	v_fmac_f32_e32 v98, v82, v82
	v_fmac_f32_e32 v99, v83, v83
	v_add_f32_e32 v98, v98, v99
	v_mul_f32_e32 v99, v88, v88
	v_fmac_f32_e32 v99, v96, v96
	v_fmac_f32_e32 v99, v92, v92
	v_fmac_f32_e32 v99, v84, v84
	v_add_f32_e32 v98, v99, v98
	v_mul_f32_e32 v99, v89, v89
	v_fmac_f32_e32 v99, v97, v97
	v_fmac_f32_e32 v99, v93, v93
	v_fmac_f32_e32 v99, v85, v85
	v_add_f32_e32 v98, v99, v98
	ds_swizzle_b32 v99, v98 offset:swizzle(SWAP,16)
	v_or_b32_e32 v103, 32, v161
	s_waitcnt lgkmcnt(0)
	v_add_f32_e32 v102, v98, v99
	v_mov_b32_e32 v104, v102
	s_nop 1
	v_permlane32_swap_b32_e32 v102, v104
	s_and_saveexec_b64 s[2:3], s[20:21]
	v_or_b32_e32 v98, 32, v160
	v_add_f32_e32 v102, v102, v104
	v_mad_u64_u32 v[98:99], s[42:43], s26, v98, v[142:143]
	v_fmaak_f32 v102, v159, v102, 0x358637bd
	v_cmp_gt_f32_e64 s[42:43], s88, v102
	v_mul_f32_e32 v104, 0x4b800000, v102
	v_mov_b32_e32 v99, v0
	v_cndmask_b32_e64 v102, v102, v104, s[42:43]
	v_rsq_f32_e32 v102, v102
	v_lshl_add_u64 v[100:101], v[98:99], 1, s[60:61]
	s_lshl_b32 s54, s16, 1
	v_lshl_add_u64 v[98:99], v[100:101], 0, s[54:55]
	v_mul_f32_e32 v104, 0x45800000, v102
	v_cndmask_b32_e64 v102, v102, v104, s[42:43]
	v_mul_f32_e32 v102, v143, v102
	v_cndmask_b32_e64 v102, v102, 1.0, s[50:51]
	v_pk_mul_f32 v[104:105], v[96:97], v[102:103] op_sel_hi:[1,0]
	v_pk_mul_f32 v[106:107], v[94:95], v[102:103] op_sel_hi:[1,0]
	global_load_dwordx4 v[180:183], v[138:139], off
	v_pk_mul_f32 v[112:113], v[90:91], v[102:103] op_sel_hi:[1,0]
	v_pk_mul_f32 v[114:115], v[92:93], v[102:103] op_sel_hi:[1,0]
	s_waitcnt vmcnt(10)
	v_pk_mul_f32 v[108:109], v[106:107], v[192:193]
	v_pk_mul_f32 v[110:111], v[104:105], v[194:195]
	v_or_b32_e32 v251, 48, v161
	v_mov_b32_e32 v218, s17
	v_cndmask_b32_e64 v218, v251, v218, s[40:41]
	v_lshlrev_b32_e32 v218, 4, v218
	v_cndmask_b32_e32 v218, 0, v218, vcc
	v_lshlrev_b32_e32 v216, 2, v218
	global_load_dwordx4 v[184:187], v216, s[22:23]
	global_load_dwordx4 v[188:191], v216, s[22:23] offset:16
	global_load_dwordx4 v[192:195], v[140:141], off
	s_waitcnt vmcnt(11)
	v_mov_b32_e32 v116, v200
	s_waitcnt vmcnt(10)
	v_pk_mul_f32 v[92:93], v[114:115], v[206:207]
	v_pk_mul_f32 v[90:91], v[112:113], v[204:205]
	v_mov_b32_e32 v112, v196
	v_mov_b32_e32 v113, v198
	v_mov_b32_e32 v117, v202
	v_mov_b32_e32 v202, v201
	v_mov_b32_e32 v198, v197
	v_pk_mul_f32 v[114:115], v[112:113], v[90:91]
	v_pk_mul_f32 v[120:121], v[116:117], v[92:93]
	v_pk_mul_f32 v[90:91], v[198:199], v[90:91]
	v_pk_mul_f32 v[92:93], v[202:203], v[92:93]
	v_pk_fma_f32 v[90:91], v[108:109], v[112:113], v[90:91] neg_lo:[0,0,1] neg_hi:[0,0,1]
	v_pk_fma_f32 v[92:93], v[110:111], v[116:117], v[92:93] neg_lo:[0,0,1] neg_hi:[0,0,1]
	v_pk_fma_f32 v[104:105], v[110:111], v[202:203], v[120:121]
	v_pk_fma_f32 v[94:95], v[108:109], v[198:199], v[114:115]
	v_cvt_pk_bf16_f32 v240, v90, v91
	v_cvt_pk_bf16_f32 v241, v92, v93
	v_cvt_pk_bf16_f32 v244, v94, v95
	v_cvt_pk_bf16_f32 v245, v104, v105
	v_pk_mul_f32 v[90:91], v[88:89], v[102:103] op_sel_hi:[1,0]
	v_pk_mul_f32 v[92:93], v[86:87], v[102:103] op_sel_hi:[1,0]
	global_load_dwordx4 v[196:199], v[138:139], off offset:16
	v_pk_mul_f32 v[104:105], v[82:83], v[102:103] op_sel_hi:[1,0]
	v_pk_mul_f32 v[106:107], v[84:85], v[102:103] op_sel_hi:[1,0]
	s_waitcnt vmcnt(10)
	v_pk_mul_f32 v[94:95], v[92:93], v[172:173]
	v_pk_mul_f32 v[96:97], v[90:91], v[174:175]
	global_load_dwordx4 v[172:175], v216, s[22:23] offset:32
	global_load_dwordx4 v[200:203], v216, s[22:23] offset:48
	global_load_dwordx4 v[204:207], v[140:141], off offset:16
	s_waitcnt vmcnt(11)
	v_mov_b32_e32 v108, v212
	s_waitcnt vmcnt(10)
	v_pk_mul_f32 v[84:85], v[106:107], v[226:227]
	v_pk_mul_f32 v[82:83], v[104:105], v[224:225]
	v_mov_b32_e32 v104, v176
	v_mov_b32_e32 v105, v178
	v_mov_b32_e32 v109, v214
	v_mov_b32_e32 v214, v213
	v_mov_b32_e32 v178, v177
	v_pk_mul_f32 v[106:107], v[104:105], v[82:83]
	v_pk_mul_f32 v[110:111], v[108:109], v[84:85]
	v_pk_mul_f32 v[82:83], v[178:179], v[82:83]
	v_pk_mul_f32 v[84:85], v[214:215], v[84:85]
	v_pk_fma_f32 v[82:83], v[94:95], v[104:105], v[82:83] neg_lo:[0,0,1] neg_hi:[0,0,1]
	v_pk_fma_f32 v[84:85], v[96:97], v[108:109], v[84:85] neg_lo:[0,0,1] neg_hi:[0,0,1]
	v_pk_fma_f32 v[90:91], v[96:97], v[214:215], v[110:111]
	v_pk_fma_f32 v[86:87], v[94:95], v[178:179], v[106:107]
	v_cvt_pk_bf16_f32 v242, v82, v83
	v_cvt_pk_bf16_f32 v243, v84, v85
	global_store_dwordx4 v[100:101], v[240:243], off
	v_cvt_pk_bf16_f32 v246, v86, v87
	v_cvt_pk_bf16_f32 v247, v90, v91
	global_store_dwordx4 v[98:99], v[244:247], off
; template <int K> __device__ __forceinline__ float swz(float v) { return __int_as_float(__builtin_amdgcn_ds_swizzle(__float_as_int(v), (K << 10) | 0x1f)); }
; __device__ __forceinline__ float x32_sum(float v) { auto r = __builtin_amdgcn_permlane32_swap(__float_as_uint(v), __float_as_uint(v), false, false); return __uint_as_float(r[0]) + __uint_as_float(r[1]); }
; __device__ __forceinline__ unsigned cvt_pk_bf16(float lo, float hi) { const f32x2c f = {lo, hi}; return __builtin_bit_cast(unsigned, __builtin_convertvector(f, bf16x2c)); }
;     __device__ __forceinline__ void operator()(const f32x4 (&acc)[2][2][4][2], const Unit& u, int wr, int wc, int, int) const {
;     ...
;             for (int m = 0; m < 4; ++m) {
;                 const int row = rowb + ai * HALF + m * 16;
;                 float ss = 0.f;
; #pragma unroll
;                 for (int j = 0; j < 4; ++j) ss += acc[ai][0][m][0][j] * acc[ai][0][m][0][j] + acc[ai][0][m][1][j] * acc[ai][0][m][1][j] + acc[ai][1][m][0][j] * acc[ai][1][m][0][j] + acc[ai][1][m][1][j] * acc[ai][1][m][1][j];
;                 ss += ::swz<16>(ss); ss = ::x32_sum(ss);
;                 float rs = rsqrtf(ss * inv_cnt + 1e-6f) * sc; rs = is_v ? 1.0f : rs;
;                 const int pos = row & 2047, pp = rot ? ((fq & 1) ? (pos & 63) : (pos >> 6)) : 0;
;                 const float* rt = rope + pp * 16;
;                 bf16_t* dst = obase + (unsigned)(row * ostride + ocol);
; #pragma unroll
;                 for (int n = 0; n < 2; ++n) {
;                     const f32x4 g1 = *(const f32x4*)(g + 4 * n), g2 = *(const f32x4*)(g + sbj + 4 * n);
;                     const f32x4 t0 = *(const f32x4*)(rt + 8 * n), t1 = *(const f32x4*)(rt + 8 * n + 4);
;                     const f32x4 c = (f32x4){t0[0], t0[2], t1[0], t1[2]}, s = (f32x4){t0[1], t0[3], t1[1], t1[3]};
;                     const f32x4 a1 = acc[ai][0][m][n] * rs * g1, a2 = acc[ai][1][m][n] * rs * g2;
;                     const f32x4 o1 = a1 * c - a2 * s, o2 = a1 * s + a2 * c;
;                     if (st_ok) { u32x2 w; w.x = cvt_pk_bf16(o1[0], o1[1]); w.y = cvt_pk_bf16(o1[2], o1[3]); *(u32x2*)(dst + 4 * n) = w;
;                         w.x = cvt_pk_bf16(o2[0], o2[1]); w.y = cvt_pk_bf16(o2[2], o2[3]); *(u32x2*)(dst + sbj + 4 * n) = w; }
;                 }
;                 asm volatile("" ::: "memory");
.LBB0_675:
	s_or_b64 exec, exec, s[2:3]
	v_mul_f32_e32 v82, v70, v70
	v_mul_f32_e32 v83, v71, v71
	v_fmac_f32_e32 v82, v78, v78
	v_fmac_f32_e32 v83, v79, v79
	v_fmac_f32_e32 v82, v74, v74
	v_fmac_f32_e32 v83, v75, v75
	v_fmac_f32_e32 v82, v66, v66
	v_fmac_f32_e32 v83, v67, v67
	v_add_f32_e32 v82, v82, v83
	v_mul_f32_e32 v83, v72, v72
	v_fmac_f32_e32 v83, v80, v80
	v_fmac_f32_e32 v83, v76, v76
	v_fmac_f32_e32 v83, v68, v68
	v_add_f32_e32 v82, v83, v82
	v_mul_f32_e32 v83, v73, v73
	v_fmac_f32_e32 v83, v81, v81
	v_fmac_f32_e32 v83, v77, v77
	v_fmac_f32_e32 v83, v69, v69
	v_add_f32_e32 v82, v83, v82
	ds_swizzle_b32 v83, v82 offset:swizzle(SWAP,16)
	v_or_b32_e32 v87, 48, v161
	s_waitcnt lgkmcnt(0)
	v_add_f32_e32 v86, v82, v83
	v_mov_b32_e32 v88, v86
	s_nop 1
	v_permlane32_swap_b32_e32 v86, v88
	s_and_saveexec_b64 s[2:3], s[20:21]
	v_or_b32_e32 v82, 48, v160
	v_add_f32_e32 v86, v86, v88
	v_mad_u64_u32 v[82:83], s[42:43], s26, v82, v[142:143]
	v_fmaak_f32 v86, v159, v86, 0x358637bd
	v_cmp_gt_f32_e64 s[42:43], s88, v86
	v_mul_f32_e32 v88, 0x4b800000, v86
	v_mov_b32_e32 v83, v0
	v_cndmask_b32_e64 v86, v86, v88, s[42:43]
	v_rsq_f32_e32 v86, v86
	v_lshl_add_u64 v[84:85], v[82:83], 1, s[60:61]
	s_lshl_b32 s54, s16, 1
	v_lshl_add_u64 v[82:83], v[84:85], 0, s[54:55]
	v_mul_f32_e32 v88, 0x45800000, v86
	v_cndmask_b32_e64 v86, v86, v88, s[42:43]
	v_mul_f32_e32 v86, v143, v86
	v_cndmask_b32_e64 v86, v86, 1.0, s[50:51]
	v_pk_mul_f32 v[88:89], v[80:81], v[86:87] op_sel_hi:[1,0]
	v_pk_mul_f32 v[90:91], v[78:79], v[86:87] op_sel_hi:[1,0]
	global_load_dwordx4 v[176:179], v[138:139], off
	v_pk_mul_f32 v[96:97], v[74:75], v[86:87] op_sel_hi:[1,0]
	v_pk_mul_f32 v[98:99], v[76:77], v[86:87] op_sel_hi:[1,0]
	s_waitcnt vmcnt(10)
	v_pk_mul_f32 v[92:93], v[90:91], v[180:181]
	v_pk_mul_f32 v[94:95], v[88:89], v[182:183]
	s_waitcnt vmcnt(8)
	v_mov_b32_e32 v100, v188
	s_waitcnt vmcnt(7)
	v_pk_mul_f32 v[76:77], v[98:99], v[194:195]
	v_pk_mul_f32 v[74:75], v[96:97], v[192:193]
	v_mov_b32_e32 v96, v184
	v_mov_b32_e32 v97, v186
	v_mov_b32_e32 v101, v190
	v_mov_b32_e32 v190, v189
	v_mov_b32_e32 v186, v185
	v_pk_mul_f32 v[98:99], v[96:97], v[74:75]
	v_pk_mul_f32 v[104:105], v[100:101], v[76:77]
	v_pk_mul_f32 v[74:75], v[186:187], v[74:75]
	v_pk_mul_f32 v[76:77], v[190:191], v[76:77]
	v_pk_fma_f32 v[74:75], v[92:93], v[96:97], v[74:75] neg_lo:[0,0,1] neg_hi:[0,0,1]
	v_pk_fma_f32 v[76:77], v[94:95], v[100:101], v[76:77] neg_lo:[0,0,1] neg_hi:[0,0,1]
	v_pk_fma_f32 v[88:89], v[94:95], v[190:191], v[104:105]
	v_pk_fma_f32 v[78:79], v[92:93], v[186:187], v[98:99]
	v_cvt_pk_bf16_f32 v240, v74, v75
	v_cvt_pk_bf16_f32 v241, v76, v77
	v_cvt_pk_bf16_f32 v244, v78, v79
	v_cvt_pk_bf16_f32 v245, v88, v89
	v_pk_mul_f32 v[74:75], v[72:73], v[86:87] op_sel_hi:[1,0]
	v_pk_mul_f32 v[76:77], v[70:71], v[86:87] op_sel_hi:[1,0]
	v_pk_mul_f32 v[88:89], v[66:67], v[86:87] op_sel_hi:[1,0]
	v_pk_mul_f32 v[90:91], v[68:69], v[86:87] op_sel_hi:[1,0]
	s_waitcnt vmcnt(6)
	v_pk_mul_f32 v[78:79], v[76:77], v[196:197]
	v_pk_mul_f32 v[80:81], v[74:75], v[198:199]
	s_waitcnt vmcnt(4)
	v_mov_b32_e32 v92, v200
	s_waitcnt vmcnt(3)
	v_pk_mul_f32 v[68:69], v[90:91], v[206:207]
	v_pk_mul_f32 v[66:67], v[88:89], v[204:205]
	v_mov_b32_e32 v88, v172
	v_mov_b32_e32 v89, v174
	v_mov_b32_e32 v93, v202
	v_mov_b32_e32 v202, v201
	v_mov_b32_e32 v174, v173
	v_pk_mul_f32 v[90:91], v[88:89], v[66:67]
	v_pk_mul_f32 v[94:95], v[92:93], v[68:69]
	v_pk_mul_f32 v[66:67], v[174:175], v[66:67]
	v_pk_mul_f32 v[68:69], v[202:203], v[68:69]
	v_pk_fma_f32 v[66:67], v[78:79], v[88:89], v[66:67] neg_lo:[0,0,1] neg_hi:[0,0,1]
	v_pk_fma_f32 v[68:69], v[80:81], v[92:93], v[68:69] neg_lo:[0,0,1] neg_hi:[0,0,1]
	v_pk_fma_f32 v[74:75], v[80:81], v[202:203], v[94:95]
	v_pk_fma_f32 v[70:71], v[78:79], v[174:175], v[90:91]
	v_cvt_pk_bf16_f32 v242, v66, v67
	v_cvt_pk_bf16_f32 v243, v68, v69
	global_store_dwordx4 v[84:85], v[240:243], off
	v_cvt_pk_bf16_f32 v246, v70, v71
	v_cvt_pk_bf16_f32 v247, v74, v75
	global_store_dwordx4 v[82:83], v[244:247], off
.LBB0_677:
	s_or_b64 exec, exec, s[2:3]
	v_mul_f32_e32 v66, v54, v54
	v_mul_f32_e32 v67, v55, v55
	v_fmac_f32_e32 v66, v62, v62
	v_fmac_f32_e32 v67, v63, v63
	v_fmac_f32_e32 v66, v58, v58
	v_fmac_f32_e32 v67, v59, v59
	v_fmac_f32_e32 v66, v50, v50
	v_fmac_f32_e32 v67, v51, v51
	v_add_f32_e32 v66, v66, v67
	v_mul_f32_e32 v67, v56, v56
	v_fmac_f32_e32 v67, v64, v64
	v_fmac_f32_e32 v67, v60, v60
	v_fmac_f32_e32 v67, v52, v52
	v_add_f32_e32 v66, v67, v66
	v_mul_f32_e32 v67, v57, v57
	v_fmac_f32_e32 v67, v65, v65
	v_fmac_f32_e32 v67, v61, v61
	v_fmac_f32_e32 v67, v53, v53
	v_add_f32_e32 v67, v67, v66
	ds_swizzle_b32 v68, v67 offset:swizzle(SWAP,16)
	v_add_u32_e32 v66, 0x80, v160
	v_bfe_u32 v71, v66, 6, 5
	v_cndmask_b32_e64 v248, v161, v71, s[40:41]
	v_lshlrev_b32_e32 v248, 4, v248
	v_cndmask_b32_e32 v248, 0, v248, vcc
	v_lshlrev_b32_e32 v249, 2, v248
	global_load_dwordx4 v[172:175], v249, s[22:23]
	global_load_dwordx4 v[180:183], v249, s[22:23] offset:16
	global_load_dwordx4 v[184:187], v[140:141], off
	global_load_dwordx4 v[188:191], v[138:139], off offset:16
	global_load_dwordx4 v[192:195], v249, s[22:23] offset:32
	global_load_dwordx4 v[196:199], v249, s[22:23] offset:48
	global_load_dwordx4 v[200:203], v[140:141], off offset:16
	s_waitcnt lgkmcnt(0)
; template <int K> __device__ __forceinline__ float swz(float v) { return __int_as_float(__builtin_amdgcn_ds_swizzle(__float_as_int(v), (K << 10) | 0x1f)); }
; __device__ __forceinline__ float x32_sum(float v) { auto r = __builtin_amdgcn_permlane32_swap(__float_as_uint(v), __float_as_uint(v), false, false); return __uint_as_float(r[0]) + __uint_as_float(r[1]); }
; __device__ __forceinline__ unsigned cvt_pk_bf16(float lo, float hi) { const f32x2c f = {lo, hi}; return __builtin_bit_cast(unsigned, __builtin_convertvector(f, bf16x2c)); }
;     __device__ __forceinline__ void operator()(const f32x4 (&acc)[2][2][4][2], const Unit& u, int wr, int wc, int, int) const {
;     ...
;             for (int m = 0; m < 4; ++m) {
;                 const int row = rowb + ai * HALF + m * 16;
;                 float ss = 0.f;
; #pragma unroll
;                 for (int j = 0; j < 4; ++j) ss += acc[ai][0][m][0][j] * acc[ai][0][m][0][j] + acc[ai][0][m][1][j] * acc[ai][0][m][1][j] + acc[ai][1][m][0][j] * acc[ai][1][m][0][j] + acc[ai][1][m][1][j] * acc[ai][1][m][1][j];
;                 ss += ::swz<16>(ss); ss = ::x32_sum(ss);
;                 float rs = rsqrtf(ss * inv_cnt + 1e-6f) * sc; rs = is_v ? 1.0f : rs;
;                 const int pos = row & 2047, pp = rot ? ((fq & 1) ? (pos & 63) : (pos >> 6)) : 0;
;                 const float* rt = rope + pp * 16;
;                 bf16_t* dst = obase + (unsigned)(row * ostride + ocol);
; #pragma unroll
;                 for (int n = 0; n < 2; ++n) {
;                     const f32x4 g1 = *(const f32x4*)(g + 4 * n), g2 = *(const f32x4*)(g + sbj + 4 * n);
;                     const f32x4 t0 = *(const f32x4*)(rt + 8 * n), t1 = *(const f32x4*)(rt + 8 * n + 4);
;                     const f32x4 c = (f32x4){t0[0], t0[2], t1[0], t1[2]}, s = (f32x4){t0[1], t0[3], t1[1], t1[3]};
;                     const f32x4 a1 = acc[ai][0][m][n] * rs * g1, a2 = acc[ai][1][m][n] * rs * g2;
;                     const f32x4 o1 = a1 * c - a2 * s, o2 = a1 * s + a2 * c;
;                     if (st_ok) { u32x2 w; w.x = cvt_pk_bf16(o1[0], o1[1]); w.y = cvt_pk_bf16(o1[2], o1[3]); *(u32x2*)(dst + 4 * n) = w;
;                         w.x = cvt_pk_bf16(o2[0], o2[1]); w.y = cvt_pk_bf16(o2[2], o2[3]); *(u32x2*)(dst + sbj + 4 * n) = w; }
;                 }
;                 asm volatile("" ::: "memory");
	v_add_f32_e32 v70, v67, v68
	v_mov_b32_e32 v72, v70
	s_nop 1
	v_permlane32_swap_b32_e32 v70, v72
	s_and_saveexec_b64 s[2:3], s[20:21]
	v_add_f32_e32 v70, v70, v72
	v_mad_u64_u32 v[66:67], s[42:43], s26, v66, v[142:143]
	v_fmaak_f32 v70, v159, v70, 0x358637bd
	v_cmp_gt_f32_e64 s[42:43], s88, v70
	v_mul_f32_e32 v72, 0x4b800000, v70
	v_mov_b32_e32 v67, v0
	v_cndmask_b32_e64 v70, v70, v72, s[42:43]
	v_rsq_f32_e32 v70, v70
	v_lshl_add_u64 v[68:69], v[66:67], 1, s[60:61]
	s_lshl_b32 s54, s16, 1
	v_lshl_add_u64 v[66:67], v[68:69], 0, s[54:55]
	v_mul_f32_e32 v72, 0x45800000, v70
	v_cndmask_b32_e64 v70, v70, v72, s[42:43]
	v_mul_f32_e32 v70, v143, v70
	v_cndmask_b32_e64 v70, v70, 1.0, s[50:51]
	v_pk_mul_f32 v[72:73], v[64:65], v[70:71] op_sel_hi:[1,0]
	v_pk_mul_f32 v[74:75], v[62:63], v[70:71] op_sel_hi:[1,0]
	global_load_dwordx4 v[204:207], v[138:139], off
	v_pk_mul_f32 v[80:81], v[58:59], v[70:71] op_sel_hi:[1,0]
	v_pk_mul_f32 v[82:83], v[60:61], v[70:71] op_sel_hi:[1,0]
	s_waitcnt vmcnt(10)
	v_pk_mul_f32 v[76:77], v[74:75], v[176:177]
	v_pk_mul_f32 v[78:79], v[72:73], v[178:179]
	v_or_b32_e32 v251, 16, v161
	v_cndmask_b32_e64 v216, v251, v71, s[40:41]
	v_lshlrev_b32_e32 v216, 4, v216
	v_cndmask_b32_e32 v216, 0, v216, vcc
	v_lshlrev_b32_e32 v216, 2, v216
	global_load_dwordx4 v[176:179], v216, s[22:23]
	global_load_dwordx4 v[212:215], v216, s[22:23] offset:16
	global_load_dwordx4 v[224:227], v[140:141], off
	s_waitcnt vmcnt(9)
	v_mov_b32_e32 v84, v180
	s_waitcnt vmcnt(8)
	v_pk_mul_f32 v[60:61], v[82:83], v[186:187]
	v_pk_mul_f32 v[58:59], v[80:81], v[184:185]
	v_mov_b32_e32 v80, v172
	v_mov_b32_e32 v81, v174
	v_mov_b32_e32 v85, v182
	v_mov_b32_e32 v182, v181
	v_mov_b32_e32 v174, v173
	v_pk_mul_f32 v[82:83], v[80:81], v[58:59]
	v_pk_mul_f32 v[88:89], v[84:85], v[60:61]
	v_pk_mul_f32 v[58:59], v[174:175], v[58:59]
	v_pk_mul_f32 v[60:61], v[182:183], v[60:61]
	v_pk_fma_f32 v[58:59], v[76:77], v[80:81], v[58:59] neg_lo:[0,0,1] neg_hi:[0,0,1]
	v_pk_fma_f32 v[60:61], v[78:79], v[84:85], v[60:61] neg_lo:[0,0,1] neg_hi:[0,0,1]
	v_pk_fma_f32 v[72:73], v[78:79], v[182:183], v[88:89]
	v_pk_fma_f32 v[62:63], v[76:77], v[174:175], v[82:83]
	v_cvt_pk_bf16_f32 v240, v58, v59
	v_cvt_pk_bf16_f32 v241, v60, v61
	v_cvt_pk_bf16_f32 v244, v62, v63
	v_cvt_pk_bf16_f32 v245, v72, v73
	v_pk_mul_f32 v[58:59], v[56:57], v[70:71] op_sel_hi:[1,0]
	v_pk_mul_f32 v[60:61], v[54:55], v[70:71] op_sel_hi:[1,0]
	global_load_dwordx4 v[172:175], v[138:139], off offset:16
	v_pk_mul_f32 v[72:73], v[50:51], v[70:71] op_sel_hi:[1,0]
	v_pk_mul_f32 v[74:75], v[52:53], v[70:71] op_sel_hi:[1,0]
	s_waitcnt vmcnt(8)
	v_pk_mul_f32 v[62:63], v[60:61], v[188:189]
	v_pk_mul_f32 v[64:65], v[58:59], v[190:191]
	global_load_dwordx4 v[180:183], v216, s[22:23] offset:32
	global_load_dwordx4 v[184:187], v216, s[22:23] offset:48
	global_load_dwordx4 v[188:191], v[140:141], off offset:16
	s_waitcnt vmcnt(9)
	v_mov_b32_e32 v76, v196
	s_waitcnt vmcnt(8)
	v_pk_mul_f32 v[52:53], v[74:75], v[202:203]
	v_pk_mul_f32 v[50:51], v[72:73], v[200:201]
	v_mov_b32_e32 v72, v192
	v_mov_b32_e32 v73, v194
	v_mov_b32_e32 v77, v198
	v_mov_b32_e32 v198, v197
	v_mov_b32_e32 v194, v193
	v_pk_mul_f32 v[74:75], v[72:73], v[50:51]
	v_pk_mul_f32 v[78:79], v[76:77], v[52:53]
	v_pk_mul_f32 v[50:51], v[194:195], v[50:51]
	v_pk_mul_f32 v[52:53], v[198:199], v[52:53]
	v_pk_fma_f32 v[50:51], v[62:63], v[72:73], v[50:51] neg_lo:[0,0,1] neg_hi:[0,0,1]
	v_pk_fma_f32 v[52:53], v[64:65], v[76:77], v[52:53] neg_lo:[0,0,1] neg_hi:[0,0,1]
	v_pk_fma_f32 v[58:59], v[64:65], v[198:199], v[78:79]
	v_pk_fma_f32 v[54:55], v[62:63], v[194:195], v[74:75]
	v_cvt_pk_bf16_f32 v242, v50, v51
	v_cvt_pk_bf16_f32 v243, v52, v53
	global_store_dwordx4 v[68:69], v[240:243], off
	v_cvt_pk_bf16_f32 v246, v54, v55
	v_cvt_pk_bf16_f32 v247, v58, v59
	global_store_dwordx4 v[66:67], v[244:247], off
.LBB0_679:
	s_or_b64 exec, exec, s[2:3]
	v_mul_f32_e32 v50, v38, v38
	v_mul_f32_e32 v51, v39, v39
	v_fmac_f32_e32 v50, v46, v46
	v_fmac_f32_e32 v51, v47, v47
	v_fmac_f32_e32 v50, v42, v42
	v_fmac_f32_e32 v51, v43, v43
	v_fmac_f32_e32 v50, v34, v34
	v_fmac_f32_e32 v51, v35, v35
	v_add_f32_e32 v50, v50, v51
	v_mul_f32_e32 v51, v40, v40
	v_fmac_f32_e32 v51, v48, v48
	v_fmac_f32_e32 v51, v44, v44
	v_fmac_f32_e32 v51, v36, v36
	v_add_f32_e32 v50, v51, v50
	v_mul_f32_e32 v51, v41, v41
	v_fmac_f32_e32 v51, v49, v49
	v_fmac_f32_e32 v51, v45, v45
	v_fmac_f32_e32 v51, v37, v37
	v_add_f32_e32 v50, v51, v50
	ds_swizzle_b32 v51, v50 offset:swizzle(SWAP,16)
	s_waitcnt lgkmcnt(0)
	v_add_f32_e32 v54, v50, v51
	v_mov_b32_e32 v55, v54
	s_nop 1
	v_permlane32_swap_b32_e32 v54, v55
	s_and_saveexec_b64 s[2:3], s[20:21]
	v_add_u32_e32 v50, 0x90, v160
	v_add_f32_e32 v54, v54, v55
	v_mad_u64_u32 v[50:51], s[42:43], s26, v50, v[142:143]
	v_fmaak_f32 v54, v159, v54, 0x358637bd
	v_cmp_gt_f32_e64 s[42:43], s88, v54
	v_mul_f32_e32 v55, 0x4b800000, v54
	v_mov_b32_e32 v51, v0
	v_cndmask_b32_e64 v54, v54, v55, s[42:43]
	v_rsq_f32_e32 v54, v54
	v_lshl_add_u64 v[52:53], v[50:51], 1, s[60:61]
	s_lshl_b32 s54, s16, 1
	v_lshl_add_u64 v[50:51], v[52:53], 0, s[54:55]
	v_mul_f32_e32 v55, 0x45800000, v54
	v_cndmask_b32_e64 v54, v54, v55, s[42:43]
	v_mul_f32_e32 v54, v143, v54
	v_cndmask_b32_e64 v54, v54, 1.0, s[50:51]
	v_pk_mul_f32 v[56:57], v[48:49], v[54:55] op_sel_hi:[1,0]
	v_pk_mul_f32 v[58:59], v[46:47], v[54:55] op_sel_hi:[1,0]
	global_load_dwordx4 v[192:195], v[138:139], off
	v_pk_mul_f32 v[64:65], v[42:43], v[54:55] op_sel_hi:[1,0]
	v_pk_mul_f32 v[66:67], v[44:45], v[54:55] op_sel_hi:[1,0]
	s_waitcnt vmcnt(10)
; template <int K> __device__ __forceinline__ float swz(float v) { return __int_as_float(__builtin_amdgcn_ds_swizzle(__float_as_int(v), (K << 10) | 0x1f)); }
; __device__ __forceinline__ float x32_sum(float v) { auto r = __builtin_amdgcn_permlane32_swap(__float_as_uint(v), __float_as_uint(v), false, false); return __uint_as_float(r[0]) + __uint_as_float(r[1]); }
; __device__ __forceinline__ unsigned cvt_pk_bf16(float lo, float hi) { const f32x2c f = {lo, hi}; return __builtin_bit_cast(unsigned, __builtin_convertvector(f, bf16x2c)); }
;     __device__ __forceinline__ void operator()(const f32x4 (&acc)[2][2][4][2], const Unit& u, int wr, int wc, int, int) const {
;     ...
;             for (int m = 0; m < 4; ++m) {
;                 const int row = rowb + ai * HALF + m * 16;
;                 float ss = 0.f;
; #pragma unroll
;                 for (int j = 0; j < 4; ++j) ss += acc[ai][0][m][0][j] * acc[ai][0][m][0][j] + acc[ai][0][m][1][j] * acc[ai][0][m][1][j] + acc[ai][1][m][0][j] * acc[ai][1][m][0][j] + acc[ai][1][m][1][j] * acc[ai][1][m][1][j];
;                 ss += ::swz<16>(ss); ss = ::x32_sum(ss);
;                 float rs = rsqrtf(ss * inv_cnt + 1e-6f) * sc; rs = is_v ? 1.0f : rs;
;                 const int pos = row & 2047, pp = rot ? ((fq & 1) ? (pos & 63) : (pos >> 6)) : 0;
;                 const float* rt = rope + pp * 16;
;                 bf16_t* dst = obase + (unsigned)(row * ostride + ocol);
; #pragma unroll
;                 for (int n = 0; n < 2; ++n) {
;                     const f32x4 g1 = *(const f32x4*)(g + 4 * n), g2 = *(const f32x4*)(g + sbj + 4 * n);
;                     const f32x4 t0 = *(const f32x4*)(rt + 8 * n), t1 = *(const f32x4*)(rt + 8 * n + 4);
;                     const f32x4 c = (f32x4){t0[0], t0[2], t1[0], t1[2]}, s = (f32x4){t0[1], t0[3], t1[1], t1[3]};
;                     const f32x4 a1 = acc[ai][0][m][n] * rs * g1, a2 = acc[ai][1][m][n] * rs * g2;
;                     const f32x4 o1 = a1 * c - a2 * s, o2 = a1 * s + a2 * c;
;                     if (st_ok) { u32x2 w; w.x = cvt_pk_bf16(o1[0], o1[1]); w.y = cvt_pk_bf16(o1[2], o1[3]); *(u32x2*)(dst + 4 * n) = w;
;                         w.x = cvt_pk_bf16(o2[0], o2[1]); w.y = cvt_pk_bf16(o2[2], o2[3]); *(u32x2*)(dst + sbj + 4 * n) = w; }
;                 }
;                 asm volatile("" ::: "memory");
	v_pk_mul_f32 v[60:61], v[58:59], v[204:205]
	v_pk_mul_f32 v[62:63], v[56:57], v[206:207]
	v_or_b32_e32 v248, 32, v161
	v_cndmask_b32_e64 v249, v248, v71, s[40:41]
	v_lshlrev_b32_e32 v249, 4, v249
	v_cndmask_b32_e32 v249, 0, v249, vcc
	v_lshlrev_b32_e32 v249, 2, v249
	global_load_dwordx4 v[196:199], v249, s[22:23]
	global_load_dwordx4 v[200:203], v249, s[22:23] offset:16
	global_load_dwordx4 v[204:207], v[140:141], off
	s_waitcnt vmcnt(11)
	v_mov_b32_e32 v68, v212
	s_waitcnt vmcnt(10)
	v_pk_mul_f32 v[44:45], v[66:67], v[226:227]
	v_pk_mul_f32 v[42:43], v[64:65], v[224:225]
	v_mov_b32_e32 v64, v176
	v_mov_b32_e32 v65, v178
	v_mov_b32_e32 v69, v214
	v_mov_b32_e32 v214, v213
	v_mov_b32_e32 v178, v177
	v_pk_mul_f32 v[66:67], v[64:65], v[42:43]
	v_pk_mul_f32 v[72:73], v[68:69], v[44:45]
	v_pk_mul_f32 v[42:43], v[178:179], v[42:43]
	v_pk_mul_f32 v[44:45], v[214:215], v[44:45]
	v_pk_fma_f32 v[42:43], v[60:61], v[64:65], v[42:43] neg_lo:[0,0,1] neg_hi:[0,0,1]
	v_pk_fma_f32 v[44:45], v[62:63], v[68:69], v[44:45] neg_lo:[0,0,1] neg_hi:[0,0,1]
	v_pk_fma_f32 v[56:57], v[62:63], v[214:215], v[72:73]
	v_pk_fma_f32 v[46:47], v[60:61], v[178:179], v[66:67]
	v_cvt_pk_bf16_f32 v240, v42, v43
	v_cvt_pk_bf16_f32 v241, v44, v45
	v_cvt_pk_bf16_f32 v244, v46, v47
	v_cvt_pk_bf16_f32 v245, v56, v57
	v_pk_mul_f32 v[42:43], v[40:41], v[54:55] op_sel_hi:[1,0]
	v_pk_mul_f32 v[44:45], v[38:39], v[54:55] op_sel_hi:[1,0]
	global_load_dwordx4 v[176:179], v[138:139], off offset:16
	v_pk_mul_f32 v[56:57], v[34:35], v[54:55] op_sel_hi:[1,0]
	s_waitcnt vmcnt(10)
	v_pk_mul_f32 v[46:47], v[44:45], v[172:173]
	v_pk_mul_f32 v[48:49], v[42:43], v[174:175]
	global_load_dwordx4 v[172:175], v249, s[22:23] offset:32
	global_load_dwordx4 v[212:215], v249, s[22:23] offset:48
	v_pk_mul_f32 v[54:55], v[36:37], v[54:55] op_sel_hi:[1,0]
	global_load_dwordx4 v[224:227], v[140:141], off offset:16
	s_waitcnt vmcnt(11)
	v_mov_b32_e32 v58, v184
	v_mov_b32_e32 v59, v186
	s_waitcnt vmcnt(10)
	v_pk_mul_f32 v[36:37], v[54:55], v[190:191]
	v_pk_mul_f32 v[34:35], v[56:57], v[188:189]
	v_mov_b32_e32 v54, v180
	v_mov_b32_e32 v55, v182
	v_mov_b32_e32 v186, v185
	v_mov_b32_e32 v182, v181
	v_pk_mul_f32 v[56:57], v[54:55], v[34:35]
	v_pk_mul_f32 v[60:61], v[58:59], v[36:37]
	v_pk_mul_f32 v[34:35], v[182:183], v[34:35]
	v_pk_mul_f32 v[36:37], v[186:187], v[36:37]
	v_pk_fma_f32 v[34:35], v[46:47], v[54:55], v[34:35] neg_lo:[0,0,1] neg_hi:[0,0,1]
	v_pk_fma_f32 v[36:37], v[48:49], v[58:59], v[36:37] neg_lo:[0,0,1] neg_hi:[0,0,1]
	v_pk_fma_f32 v[42:43], v[48:49], v[186:187], v[60:61]
	v_pk_fma_f32 v[38:39], v[46:47], v[182:183], v[56:57]
	v_cvt_pk_bf16_f32 v242, v34, v35
	v_cvt_pk_bf16_f32 v243, v36, v37
	global_store_dwordx4 v[52:53], v[240:243], off
	v_cvt_pk_bf16_f32 v246, v38, v39
	v_cvt_pk_bf16_f32 v247, v42, v43
	global_store_dwordx4 v[50:51], v[244:247], off
.LBB0_681:
	s_or_b64 exec, exec, s[2:3]
	v_mul_f32_e32 v34, v22, v22
	v_mul_f32_e32 v35, v23, v23
	v_fmac_f32_e32 v34, v30, v30
	v_fmac_f32_e32 v35, v31, v31
	v_fmac_f32_e32 v34, v26, v26
	v_fmac_f32_e32 v35, v27, v27
	v_fmac_f32_e32 v34, v18, v18
	v_fmac_f32_e32 v35, v19, v19
	v_add_f32_e32 v34, v34, v35
	v_mul_f32_e32 v35, v24, v24
	v_fmac_f32_e32 v35, v32, v32
	v_fmac_f32_e32 v35, v28, v28
	v_fmac_f32_e32 v35, v20, v20
	v_add_f32_e32 v34, v35, v34
	v_mul_f32_e32 v35, v25, v25
	v_fmac_f32_e32 v35, v33, v33
	v_fmac_f32_e32 v35, v29, v29
	v_fmac_f32_e32 v35, v21, v21
	v_add_f32_e32 v34, v35, v34
	ds_swizzle_b32 v35, v34 offset:swizzle(SWAP,16)
	s_waitcnt lgkmcnt(0)
	v_add_f32_e32 v38, v34, v35
	v_mov_b32_e32 v39, v38
	s_nop 1
	v_permlane32_swap_b32_e32 v38, v39
	s_and_saveexec_b64 s[2:3], s[20:21]
	v_add_u32_e32 v34, 0xa0, v160
	v_add_f32_e32 v38, v38, v39
	v_mad_u64_u32 v[34:35], s[42:43], s26, v34, v[142:143]
	v_fmaak_f32 v38, v159, v38, 0x358637bd
	v_cmp_gt_f32_e64 s[42:43], s88, v38
	v_mul_f32_e32 v39, 0x4b800000, v38
	v_mov_b32_e32 v35, v0
	v_cndmask_b32_e64 v38, v38, v39, s[42:43]
	v_rsq_f32_e32 v38, v38
	v_lshl_add_u64 v[36:37], v[34:35], 1, s[60:61]
	s_lshl_b32 s54, s16, 1
	v_lshl_add_u64 v[34:35], v[36:37], 0, s[54:55]
	v_mul_f32_e32 v39, 0x45800000, v38
	v_cndmask_b32_e64 v38, v38, v39, s[42:43]
	v_mul_f32_e32 v38, v143, v38
	v_cndmask_b32_e64 v38, v38, 1.0, s[50:51]
	v_pk_mul_f32 v[40:41], v[32:33], v[38:39] op_sel_hi:[1,0]
	v_pk_mul_f32 v[42:43], v[30:31], v[38:39] op_sel_hi:[1,0]
	global_load_dwordx4 v[180:183], v[138:139], off
	v_pk_mul_f32 v[48:49], v[26:27], v[38:39] op_sel_hi:[1,0]
	v_pk_mul_f32 v[50:51], v[28:29], v[38:39] op_sel_hi:[1,0]
	s_waitcnt vmcnt(10)
	v_pk_mul_f32 v[44:45], v[42:43], v[192:193]
	v_pk_mul_f32 v[46:47], v[40:41], v[194:195]
	v_or_b32_e32 v251, 48, v161
	v_cndmask_b32_e64 v216, v251, v71, s[40:41]
	v_lshlrev_b32_e32 v216, 4, v216
	v_cndmask_b32_e32 v216, 0, v216, vcc
	v_lshlrev_b32_e32 v216, 2, v216
	global_load_dwordx4 v[184:187], v216, s[22:23]
	global_load_dwordx4 v[188:191], v216, s[22:23] offset:16
	global_load_dwordx4 v[192:195], v[140:141], off
	s_waitcnt vmcnt(11)
	v_mov_b32_e32 v52, v200
	s_waitcnt vmcnt(10)
	v_pk_mul_f32 v[28:29], v[50:51], v[206:207]
	v_pk_mul_f32 v[26:27], v[48:49], v[204:205]
	v_mov_b32_e32 v48, v196
	v_mov_b32_e32 v49, v198
	v_mov_b32_e32 v53, v202
	v_mov_b32_e32 v202, v201
	v_mov_b32_e32 v198, v197
	v_pk_mul_f32 v[50:51], v[48:49], v[26:27]
	v_pk_mul_f32 v[54:55], v[52:53], v[28:29]
	v_pk_mul_f32 v[26:27], v[198:199], v[26:27]
	v_pk_mul_f32 v[28:29], v[202:203], v[28:29]
	v_pk_fma_f32 v[26:27], v[44:45], v[48:49], v[26:27] neg_lo:[0,0,1] neg_hi:[0,0,1]
	v_pk_fma_f32 v[28:29], v[46:47], v[52:53], v[28:29] neg_lo:[0,0,1] neg_hi:[0,0,1]
	v_pk_fma_f32 v[40:41], v[46:47], v[202:203], v[54:55]
	v_pk_fma_f32 v[30:31], v[44:45], v[198:199], v[50:51]
	v_cvt_pk_bf16_f32 v240, v26, v27
	v_cvt_pk_bf16_f32 v241, v28, v29
	v_cvt_pk_bf16_f32 v244, v30, v31
	v_cvt_pk_bf16_f32 v245, v40, v41
	v_pk_mul_f32 v[26:27], v[24:25], v[38:39] op_sel_hi:[1,0]
	v_pk_mul_f32 v[28:29], v[22:23], v[38:39] op_sel_hi:[1,0]
	global_load_dwordx4 v[196:199], v[138:139], off offset:16
	v_pk_mul_f32 v[40:41], v[18:19], v[38:39] op_sel_hi:[1,0]
	s_waitcnt vmcnt(10)
; template <int K> __device__ __forceinline__ float swz(float v) { return __int_as_float(__builtin_amdgcn_ds_swizzle(__float_as_int(v), (K << 10) | 0x1f)); }
; __device__ __forceinline__ float x32_sum(float v) { auto r = __builtin_amdgcn_permlane32_swap(__float_as_uint(v), __float_as_uint(v), false, false); return __uint_as_float(r[0]) + __uint_as_float(r[1]); }
; __device__ __forceinline__ unsigned cvt_pk_bf16(float lo, float hi) { const f32x2c f = {lo, hi}; return __builtin_bit_cast(unsigned, __builtin_convertvector(f, bf16x2c)); }
;     __device__ __forceinline__ void operator()(const f32x4 (&acc)[2][2][4][2], const Unit& u, int wr, int wc, int, int) const {
;     ...
;             for (int m = 0; m < 4; ++m) {
;                 const int row = rowb + ai * HALF + m * 16;
;                 float ss = 0.f;
; #pragma unroll
;                 for (int j = 0; j < 4; ++j) ss += acc[ai][0][m][0][j] * acc[ai][0][m][0][j] + acc[ai][0][m][1][j] * acc[ai][0][m][1][j] + acc[ai][1][m][0][j] * acc[ai][1][m][0][j] + acc[ai][1][m][1][j] * acc[ai][1][m][1][j];
;                 ss += ::swz<16>(ss); ss = ::x32_sum(ss);
;                 float rs = rsqrtf(ss * inv_cnt + 1e-6f) * sc; rs = is_v ? 1.0f : rs;
;                 const int pos = row & 2047, pp = rot ? ((fq & 1) ? (pos & 63) : (pos >> 6)) : 0;
;                 const float* rt = rope + pp * 16;
;                 bf16_t* dst = obase + (unsigned)(row * ostride + ocol);
; #pragma unroll
;                 for (int n = 0; n < 2; ++n) {
;                     const f32x4 g1 = *(const f32x4*)(g + 4 * n), g2 = *(const f32x4*)(g + sbj + 4 * n);
;                     const f32x4 t0 = *(const f32x4*)(rt + 8 * n), t1 = *(const f32x4*)(rt + 8 * n + 4);
;                     const f32x4 c = (f32x4){t0[0], t0[2], t1[0], t1[2]}, s = (f32x4){t0[1], t0[3], t1[1], t1[3]};
;                     const f32x4 a1 = acc[ai][0][m][n] * rs * g1, a2 = acc[ai][1][m][n] * rs * g2;
;                     const f32x4 o1 = a1 * c - a2 * s, o2 = a1 * s + a2 * c;
;                     if (st_ok) { u32x2 w; w.x = cvt_pk_bf16(o1[0], o1[1]); w.y = cvt_pk_bf16(o1[2], o1[3]); *(u32x2*)(dst + 4 * n) = w;
;                         w.x = cvt_pk_bf16(o2[0], o2[1]); w.y = cvt_pk_bf16(o2[2], o2[3]); *(u32x2*)(dst + sbj + 4 * n) = w; }
;                 }
;                 asm volatile("" ::: "memory");
	v_pk_mul_f32 v[30:31], v[28:29], v[176:177]
	v_pk_mul_f32 v[32:33], v[26:27], v[178:179]
	global_load_dwordx4 v[176:179], v216, s[22:23] offset:32
	global_load_dwordx4 v[200:203], v216, s[22:23] offset:48
	v_pk_mul_f32 v[38:39], v[20:21], v[38:39] op_sel_hi:[1,0]
	global_load_dwordx4 v[204:207], v[140:141], off offset:16
	s_waitcnt vmcnt(11)
	v_mov_b32_e32 v42, v212
	v_mov_b32_e32 v43, v214
	s_waitcnt vmcnt(10)
	v_pk_mul_f32 v[20:21], v[38:39], v[226:227]
	v_pk_mul_f32 v[18:19], v[40:41], v[224:225]
	v_mov_b32_e32 v38, v172
	v_mov_b32_e32 v39, v174
	v_mov_b32_e32 v214, v213
	v_mov_b32_e32 v174, v173
	v_pk_mul_f32 v[40:41], v[38:39], v[18:19]
	v_pk_mul_f32 v[44:45], v[42:43], v[20:21]
	v_pk_mul_f32 v[18:19], v[174:175], v[18:19]
	v_pk_mul_f32 v[20:21], v[214:215], v[20:21]
	v_pk_fma_f32 v[18:19], v[30:31], v[38:39], v[18:19] neg_lo:[0,0,1] neg_hi:[0,0,1]
	v_pk_fma_f32 v[20:21], v[32:33], v[42:43], v[20:21] neg_lo:[0,0,1] neg_hi:[0,0,1]
	v_pk_fma_f32 v[26:27], v[32:33], v[214:215], v[44:45]
	v_pk_fma_f32 v[22:23], v[30:31], v[174:175], v[40:41]
	v_cvt_pk_bf16_f32 v242, v18, v19
	v_cvt_pk_bf16_f32 v243, v20, v21
	global_store_dwordx4 v[36:37], v[240:243], off
	v_cvt_pk_bf16_f32 v246, v22, v23
	v_cvt_pk_bf16_f32 v247, v26, v27
	global_store_dwordx4 v[34:35], v[244:247], off
.LBB0_683:
	s_or_b64 exec, exec, s[2:3]
	v_mul_f32_e32 v18, v6, v6
	v_mul_f32_e32 v19, v7, v7
	v_fmac_f32_e32 v18, v14, v14
	v_fmac_f32_e32 v19, v15, v15
	v_fmac_f32_e32 v18, v10, v10
	v_fmac_f32_e32 v19, v11, v11
	v_fmac_f32_e32 v18, v2, v2
	v_fmac_f32_e32 v19, v3, v3
	v_add_f32_e32 v18, v18, v19
	v_mul_f32_e32 v19, v8, v8
	v_fmac_f32_e32 v19, v16, v16
	v_fmac_f32_e32 v19, v12, v12
	v_fmac_f32_e32 v19, v4, v4
	v_add_f32_e32 v18, v19, v18
	v_mul_f32_e32 v19, v9, v9
	v_fmac_f32_e32 v19, v17, v17
	v_fmac_f32_e32 v19, v13, v13
	v_fmac_f32_e32 v19, v5, v5
	v_add_f32_e32 v18, v19, v18
	ds_swizzle_b32 v19, v18 offset:swizzle(SWAP,16)
	s_waitcnt lgkmcnt(0)
	v_add_f32_e32 v22, v18, v19
	v_mov_b32_e32 v23, v22
	s_nop 1
	v_permlane32_swap_b32_e32 v22, v23
	s_and_saveexec_b64 s[2:3], s[20:21]
	v_add_f32_e32 v22, v22, v23
	v_fmaak_f32 v22, v159, v22, 0x358637bd
	v_cmp_gt_f32_e64 s[42:43], s88, v22
	v_mul_f32_e32 v23, 0x4b800000, v22
	v_add_u32_e32 v18, 0xb0, v160
	v_cndmask_b32_e64 v22, v22, v23, s[42:43]
	v_rsq_f32_e32 v22, v22
	v_mad_u64_u32 v[18:19], s[20:21], s26, v18, v[142:143]
	v_mov_b32_e32 v19, v0
	v_mul_f32_e32 v23, 0x45800000, v22
	v_cndmask_b32_e64 v22, v22, v23, s[42:43]
	v_mul_f32_e32 v22, v143, v22
	v_cndmask_b32_e64 v22, v22, 1.0, s[50:51]
	v_pk_mul_f32 v[24:25], v[16:17], v[22:23] op_sel_hi:[1,0]
	v_pk_mul_f32 v[26:27], v[14:15], v[22:23] op_sel_hi:[1,0]
	v_pk_mul_f32 v[32:33], v[10:11], v[22:23] op_sel_hi:[1,0]
	v_pk_mul_f32 v[34:35], v[12:13], v[22:23] op_sel_hi:[1,0]
	v_lshl_add_u64 v[20:21], v[18:19], 1, s[60:61]
	s_lshl_b32 s54, s16, 1
	v_lshl_add_u64 v[18:19], v[20:21], 0, s[54:55]
	s_waitcnt vmcnt(9)
	v_pk_mul_f32 v[28:29], v[26:27], v[180:181]
	v_pk_mul_f32 v[30:31], v[24:25], v[182:183]
	s_waitcnt vmcnt(7)
	v_mov_b32_e32 v36, v188
	s_waitcnt vmcnt(6)
	v_pk_mul_f32 v[12:13], v[34:35], v[194:195]
	v_pk_mul_f32 v[10:11], v[32:33], v[192:193]
	v_mov_b32_e32 v32, v184
	v_mov_b32_e32 v33, v186
	v_mov_b32_e32 v37, v190
	v_mov_b32_e32 v190, v189
	v_mov_b32_e32 v186, v185
	v_pk_mul_f32 v[34:35], v[32:33], v[10:11]
	v_pk_mul_f32 v[38:39], v[36:37], v[12:13]
	v_pk_mul_f32 v[10:11], v[186:187], v[10:11]
	v_pk_mul_f32 v[12:13], v[190:191], v[12:13]
	v_pk_fma_f32 v[10:11], v[28:29], v[32:33], v[10:11] neg_lo:[0,0,1] neg_hi:[0,0,1]
	v_pk_fma_f32 v[12:13], v[30:31], v[36:37], v[12:13] neg_lo:[0,0,1] neg_hi:[0,0,1]
	v_pk_fma_f32 v[24:25], v[30:31], v[190:191], v[38:39]
	v_pk_fma_f32 v[14:15], v[28:29], v[186:187], v[34:35]
	v_cvt_pk_bf16_f32 v240, v10, v11
	v_cvt_pk_bf16_f32 v241, v12, v13
	v_cvt_pk_bf16_f32 v244, v14, v15
	v_cvt_pk_bf16_f32 v245, v24, v25
	v_pk_mul_f32 v[10:11], v[8:9], v[22:23] op_sel_hi:[1,0]
	v_pk_mul_f32 v[12:13], v[6:7], v[22:23] op_sel_hi:[1,0]
	v_pk_mul_f32 v[24:25], v[2:3], v[22:23] op_sel_hi:[1,0]
	s_waitcnt vmcnt(5)
	v_pk_mul_f32 v[14:15], v[12:13], v[196:197]
	v_pk_mul_f32 v[16:17], v[10:11], v[198:199]
	v_pk_mul_f32 v[22:23], v[4:5], v[22:23] op_sel_hi:[1,0]
	s_waitcnt vmcnt(3)
	v_mov_b32_e32 v26, v200
	v_mov_b32_e32 v27, v202
	s_waitcnt vmcnt(2)
	v_pk_mul_f32 v[4:5], v[22:23], v[206:207]
	v_pk_mul_f32 v[2:3], v[24:25], v[204:205]
	v_mov_b32_e32 v22, v176
	v_mov_b32_e32 v23, v178
	v_mov_b32_e32 v202, v201
	v_mov_b32_e32 v178, v177
	v_pk_mul_f32 v[24:25], v[22:23], v[2:3]
	v_pk_mul_f32 v[28:29], v[26:27], v[4:5]
	v_pk_mul_f32 v[2:3], v[178:179], v[2:3]
	v_pk_mul_f32 v[4:5], v[202:203], v[4:5]
	v_pk_fma_f32 v[2:3], v[14:15], v[22:23], v[2:3] neg_lo:[0,0,1] neg_hi:[0,0,1]
	v_pk_fma_f32 v[4:5], v[16:17], v[26:27], v[4:5] neg_lo:[0,0,1] neg_hi:[0,0,1]
	v_pk_fma_f32 v[10:11], v[16:17], v[202:203], v[28:29]
	v_pk_fma_f32 v[6:7], v[14:15], v[178:179], v[24:25]
	v_cvt_pk_bf16_f32 v242, v2, v3
	v_cvt_pk_bf16_f32 v243, v4, v5
	global_store_dwordx4 v[20:21], v[240:243], off
	v_cvt_pk_bf16_f32 v246, v6, v7
	v_cvt_pk_bf16_f32 v247, v10, v11
	global_store_dwordx4 v[18:19], v[244:247], off
	s_branch .LBB0_650
